# attention: static priority for blocks >= 256 (co-resident block interleave), per-section setprio flips removed
# speedup vs baseline: 1.0010x; 1.0010x over previous
; __device__ __forceinline__ void ph_attn(const P& p, int need_ctx, char* smem) {
;     ...
;   const int tid = (threadIdx.x + zz), lane = tid & 63, wave = tid >> 6, lr = lane & 15, lq = lane >> 4;
;   int ntask = 8 * 4 * 16 + (need_ctx ? 8 * 4 * 2 : 0);
;   for (int task = (blockIdx.x + zz); task < ntask; task += (gridDim.x + zz)) {
;     int b, h, qrow0, nkt;
;     if (task < 512) { b = task >> 6; h = (task >> 4) & 3; int qt = task & 15; qrow0 = b * 2048 + qt * 128; nkt = 36; }
;     else { int t2 = task - 512; b = t2 >> 3; h = (t2 >> 1) & 3; int qt = t2 & 1; qrow0 = T_LAT + b * 256 + qt * 128; nkt = 4; }
.LBB0_1239:
	s_or_b64 exec, exec, s[6:7]
	s_and_b64 s[0:1], s[40:41], exec
	s_movk_i32 s0, 0x240
	s_mov_b32 s20, 0
	s_cselect_b32 s16, 0x200, s0
	s_add_i32 s17, s20, s87
	v_mov_b32_e32 v196, 0x80
	s_cmp_ge_i32 s17, s16
	s_cbranch_scc1 .LBB0_1262
	s_cmpk_lt_u32 s87, 0x100
	s_cbranch_scc1 .Latt_noprio
	s_setprio 1

; DEV f32x4 mfma16(bf16x8 a, bf16x8 b, f32x4 c) { return __builtin_amdgcn_mfma_f32_16x16x32_bf16(a, b, c, 0, 0, 0); }
; __device__ __forceinline__ void ph_attn(const P& p, int need_ctx, char* smem) {
;     ...
;       f32x4 s[2][4];
;       __builtin_amdgcn_s_setprio(1);
; #pragma unroll
;       for (int nt = 0; nt < 4; nt++) {
;         s[0][nt] = (f32x4){0.f, 0.f, 0.f, 0.f}; s[1][nt] = (f32x4){0.f, 0.f, 0.f, 0.f};
; #pragma unroll
;         for (int ks = 0; ks < 3; ks++) {
;           bf16x8 kf = *(const bf16x8*)(sK + (nt * 16 + lr) * 104 + ks * 32 + lq * 8);
;           s[0][nt] = mfma16(kf, qf[0][ks], s[0][nt]);
;           s[1][nt] = mfma16(kf, qf[1][ks], s[1][nt]);
;         }
;       }
;       __builtin_amdgcn_s_setprio(0);
;       bf16x8 pf[2][2];
; #pragma unroll
;       for (int qs = 0; qs < 2; qs++) {
;         float mx = s[qs][0][0];
; #pragma unroll
;         for (int nt = 0; nt < 4; nt++)
; #pragma unroll
;           for (int r = 0; r < 4; r++) mx = fmaxf(mx, s[qs][nt][r]);
;         mx = fmaxf(mx, __shfl_xor(mx, 16, 64)); mx = fmaxf(mx, __shfl_xor(mx, 32, 64));
;         float mn = fmaxf(m[qs], mx);
;         float alpha = __builtin_amdgcn_exp2f(m[qs] - mn);
;         m[qs] = mn;
;         float ps = 0.f;
; #pragma unroll
;         for (int nt = 0; nt < 4; nt++)
; #pragma unroll
;           for (int r = 0; r < 4; r++) { float e = __builtin_amdgcn_exp2f(s[qs][nt][r] - mn); s[qs][nt][r] = e; ps += e; }
;         lsum[qs] = lsum[qs] * alpha + ps;
.LBB0_1259:
	ds_read_b128 v[142:145], v129
	ds_read_b128 v[150:153], v129 offset:64
	s_waitcnt lgkmcnt(1)
	v_mfma_f32_16x16x32_bf16 v[146:149], v[142:145], v[0:3], 0
	ds_read_b128 v[158:161], v129 offset:3392
	ds_read_b128 v[166:169], v129 offset:6720
	ds_read_b128 v[174:177], v129 offset:10048
	v_mfma_f32_16x16x32_bf16 v[142:145], v[142:145], v[12:15], 0
	s_waitcnt lgkmcnt(3)
	v_mfma_f32_16x16x32_bf16 v[146:149], v[150:153], v[4:7], v[146:149]
	v_mfma_f32_16x16x32_bf16 v[142:145], v[150:153], v[16:19], v[142:145]
	ds_read_b128 v[150:153], v129 offset:128
	s_waitcnt lgkmcnt(0)
	v_mfma_f32_16x16x32_bf16 v[146:149], v[150:153], v[8:11], v[146:149]
	v_mfma_f32_16x16x32_bf16 v[142:145], v[150:153], v[20:23], v[142:145]
	ds_read_b128 v[150:153], v129 offset:3328
	s_waitcnt lgkmcnt(0)
	v_mfma_f32_16x16x32_bf16 v[154:157], v[150:153], v[0:3], 0
	v_mfma_f32_16x16x32_bf16 v[150:153], v[150:153], v[12:15], 0
	v_mfma_f32_16x16x32_bf16 v[154:157], v[158:161], v[4:7], v[154:157]
	v_mfma_f32_16x16x32_bf16 v[150:153], v[158:161], v[16:19], v[150:153]
	ds_read_b128 v[158:161], v129 offset:3456
	s_waitcnt lgkmcnt(0)
	v_mfma_f32_16x16x32_bf16 v[154:157], v[158:161], v[8:11], v[154:157]
	v_mfma_f32_16x16x32_bf16 v[150:153], v[158:161], v[20:23], v[150:153]
	ds_read_b128 v[158:161], v129 offset:6656
	s_waitcnt lgkmcnt(0)
	v_mfma_f32_16x16x32_bf16 v[162:165], v[158:161], v[0:3], 0
	v_mfma_f32_16x16x32_bf16 v[158:161], v[158:161], v[12:15], 0
	v_mfma_f32_16x16x32_bf16 v[162:165], v[166:169], v[4:7], v[162:165]
	v_mfma_f32_16x16x32_bf16 v[158:161], v[166:169], v[16:19], v[158:161]
	ds_read_b128 v[166:169], v129 offset:6784
	s_waitcnt lgkmcnt(0)
	v_mfma_f32_16x16x32_bf16 v[162:165], v[166:169], v[8:11], v[162:165]
	v_mfma_f32_16x16x32_bf16 v[158:161], v[166:169], v[20:23], v[158:161]
	ds_read_b128 v[166:169], v129 offset:9984
	s_waitcnt lgkmcnt(0)
	v_mfma_f32_16x16x32_bf16 v[170:173], v[166:169], v[0:3], 0
	v_mfma_f32_16x16x32_bf16 v[166:169], v[166:169], v[12:15], 0
	v_mfma_f32_16x16x32_bf16 v[170:173], v[174:177], v[4:7], v[170:173]
	v_mfma_f32_16x16x32_bf16 v[166:169], v[174:177], v[16:19], v[166:169]
	ds_read_b128 v[174:177], v129 offset:10112
	s_waitcnt lgkmcnt(0)
	v_mfma_f32_16x16x32_bf16 v[170:173], v[174:177], v[8:11], v[170:173]
	v_mfma_f32_16x16x32_bf16 v[166:169], v[174:177], v[20:23], v[166:169]
	v_max_f32_e32 v141, v147, v147
	v_max_f32_e32 v174, v146, v146
	v_max_f32_e32 v141, v174, v141
	v_max3_f32 v141, v141, v148, v149
	v_max3_f32 v141, v141, v154, v155
	v_max3_f32 v141, v141, v156, v157
	v_max3_f32 v141, v141, v162, v163
	v_max3_f32 v141, v141, v164, v165
	v_max3_f32 v141, v141, v170, v171
	v_max3_f32 v141, v141, v172, v173
	ds_bpermute_b32 v174, v97, v141
	s_waitcnt lgkmcnt(0)
	v_max_f32_e32 v174, v174, v174
	v_max_f32_e32 v141, v141, v174
	ds_bpermute_b32 v174, v99, v141
	s_waitcnt lgkmcnt(0)
	v_max3_f32 v194, v140, v141, v174
	v_sub_f32_e32 v140, v140, v194
	v_sub_f32_e32 v141, v146, v194
	v_sub_f32_e32 v146, v147, v194
	v_sub_f32_e32 v147, v148, v194
	v_exp_f32_e32 v148, v140
	v_sub_f32_e32 v140, v154, v194
	v_exp_f32_e32 v154, v140
	v_sub_f32_e32 v140, v155, v194
	v_exp_f32_e32 v182, v140
	v_sub_f32_e32 v140, v156, v194
	v_exp_f32_e32 v156, v140
	v_sub_f32_e32 v140, v157, v194
	v_exp_f32_e32 v184, v140
	v_sub_f32_e32 v140, v162, v194
	v_exp_f32_e32 v162, v140
	v_sub_f32_e32 v140, v163, v194
	v_exp_f32_e32 v186, v140
	v_sub_f32_e32 v140, v164, v194
	v_exp_f32_e32 v164, v140
	v_sub_f32_e32 v140, v165, v194
	v_exp_f32_e32 v174, v141
	v_exp_f32_e32 v188, v140
	v_max_f32_e32 v140, v143, v143
	v_max_f32_e32 v141, v142, v142
	v_max_f32_e32 v140, v141, v140
	v_max3_f32 v140, v140, v144, v145
	v_max3_f32 v140, v140, v150, v151
	v_max3_f32 v140, v140, v152, v153
	v_max3_f32 v140, v140, v158, v159
	v_max3_f32 v140, v140, v160, v161
	v_max3_f32 v140, v140, v166, v167
	v_max3_f32 v140, v140, v168, v169
	ds_bpermute_b32 v141, v97, v140
	v_sub_f32_e32 v149, v149, v194
	v_exp_f32_e32 v180, v149
	v_exp_f32_e32 v176, v146
	v_exp_f32_e32 v178, v147
	s_waitcnt lgkmcnt(0)
	v_max_f32_e32 v141, v141, v141
	v_max_f32_e32 v140, v140, v141
	ds_bpermute_b32 v141, v99, v140
	v_sub_f32_e32 v146, v170, v194
	v_exp_f32_e32 v170, v146
	v_sub_f32_e32 v146, v171, v194
	v_exp_f32_e32 v190, v146
	s_waitcnt lgkmcnt(0)
; DEV f32x4 mfma16(bf16x8 a, bf16x8 b, f32x4 c) { return __builtin_amdgcn_mfma_f32_16x16x32_bf16(a, b, c, 0, 0, 0); }
; __device__ __forceinline__ void ph_attn(const P& p, int need_ctx, char* smem) {
;     ...
;         mx = fmaxf(mx, __shfl_xor(mx, 16, 64)); mx = fmaxf(mx, __shfl_xor(mx, 32, 64));
;         float mn = fmaxf(m[qs], mx);
;         float alpha = __builtin_amdgcn_exp2f(m[qs] - mn);
;         m[qs] = mn;
;         float ps = 0.f;
; #pragma unroll
;         for (int nt = 0; nt < 4; nt++)
; #pragma unroll
;           for (int r = 0; r < 4; r++) { float e = __builtin_amdgcn_exp2f(s[qs][nt][r] - mn); s[qs][nt][r] = e; ps += e; }
;         lsum[qs] = lsum[qs] * alpha + ps;
; #pragma unroll
;         for (int nt = 0; nt < 4; nt++)
; #pragma unroll
;           for (int r = 0; r < 4; r++) o[qs][nt][r] *= alpha;
; #pragma unroll
;         for (int m2 = 0; m2 < 2; m2++) {
;           u32x4 w;
;           w[0] = pack2(s[qs][2 * m2][0], s[qs][2 * m2][1]); w[1] = pack2(s[qs][2 * m2][2], s[qs][2 * m2][3]);
;           w[2] = pack2(s[qs][2 * m2 + 1][0], s[qs][2 * m2 + 1][1]); w[3] = pack2(s[qs][2 * m2 + 1][2], s[qs][2 * m2 + 1][3]);
;           pf[qs][m2] = __builtin_bit_cast(bf16x8, w);
;         }
;       }
;       __builtin_amdgcn_s_setprio(1);
; #pragma unroll
;       for (int m2 = 0; m2 < 2; m2++) {
; #pragma unroll
;         for (int nt = 0; nt < 4; nt++) {
;           const u16* vp = sV + (nt * 16 + lr) * 72 + 32 * m2 + 4 * lq;
;           uint2 lo = *(const uint2*)vp, hi = *(const uint2*)(vp + 16);
;           u32x4 w; w[0] = lo.x; w[1] = lo.y; w[2] = hi.x; w[3] = hi.y;
;           bf16x8 vf = __builtin_bit_cast(bf16x8, w);
;           o[0][nt] = mfma16(vf, pf[0][m2], o[0][nt]);
;           o[1][nt] = mfma16(vf, pf[1][m2], o[1][nt]);
;         }
;       }
;       __builtin_amdgcn_s_setprio(0);
	v_max3_f32 v195, v135, v140, v141
	v_sub_f32_e32 v135, v135, v195
	v_exp_f32_e32 v149, v135
	v_sub_f32_e32 v135, v142, v195
	v_exp_f32_e32 v175, v135
	v_sub_f32_e32 v135, v143, v195
	v_exp_f32_e32 v177, v135
	v_sub_f32_e32 v135, v144, v195
	v_exp_f32_e32 v179, v135
	v_sub_f32_e32 v135, v145, v195
	v_exp_f32_e32 v181, v135
	v_sub_f32_e32 v135, v150, v195
	v_exp_f32_e32 v155, v135
	v_sub_f32_e32 v135, v151, v195
	v_pk_add_f32 v[144:145], v[174:175], 0 op_sel_hi:[1,0]
	v_exp_f32_e32 v183, v135
	v_pk_add_f32 v[144:145], v[176:177], v[144:145]
	v_sub_f32_e32 v135, v152, v195
	v_pk_add_f32 v[144:145], v[178:179], v[144:145]
	v_exp_f32_e32 v157, v135
	v_sub_f32_e32 v135, v153, v195
	v_pk_add_f32 v[144:145], v[180:181], v[144:145]
	v_exp_f32_e32 v185, v135
	v_sub_f32_e32 v135, v158, v195
	v_pk_add_f32 v[144:145], v[154:155], v[144:145]
	v_exp_f32_e32 v163, v135
	v_sub_f32_e32 v135, v159, v195
	v_pk_add_f32 v[150:151], v[182:183], v[144:145]
	v_exp_f32_e32 v187, v135
	v_sub_f32_e32 v135, v160, v195
	v_exp_f32_e32 v165, v135
	v_sub_f32_e32 v135, v161, v195
	v_pk_add_f32 v[150:151], v[156:157], v[150:151]
	v_exp_f32_e32 v189, v135
	v_sub_f32_e32 v135, v166, v195
	v_pk_add_f32 v[150:151], v[184:185], v[150:151]
	v_exp_f32_e32 v171, v135
	v_sub_f32_e32 v135, v167, v195
	v_pk_add_f32 v[150:151], v[162:163], v[150:151]
	v_sub_f32_e32 v146, v172, v194
	v_exp_f32_e32 v191, v135
	v_sub_f32_e32 v135, v168, v195
	v_pk_add_f32 v[150:151], v[186:187], v[150:151]
	v_exp_f32_e32 v172, v146
	v_sub_f32_e32 v146, v173, v194
	v_exp_f32_e32 v173, v135
	v_sub_f32_e32 v135, v169, v195
	v_pk_add_f32 v[150:151], v[164:165], v[150:151]
	v_exp_f32_e32 v192, v146
	v_exp_f32_e32 v193, v135
	v_pk_add_f32 v[150:151], v[188:189], v[150:151]
	v_pk_mul_f32 v[74:75], v[74:75], v[148:149] op_sel_hi:[1,0]
	v_pk_add_f32 v[150:151], v[170:171], v[150:151]
	v_pk_mul_f32 v[72:73], v[72:73], v[148:149] op_sel_hi:[1,0]
	v_pk_add_f32 v[150:151], v[190:191], v[150:151]
	v_pk_mul_f32 v[70:71], v[70:71], v[148:149] op_sel_hi:[1,0]
	v_pk_add_f32 v[150:151], v[172:173], v[150:151]
	v_pk_mul_f32 v[68:69], v[68:69], v[148:149] op_sel_hi:[1,0]
	v_pk_add_f32 v[150:151], v[192:193], v[150:151]
	v_pk_mul_f32 v[66:67], v[66:67], v[148:149] op_sel_hi:[1,0]
	v_pk_mul_f32 v[64:65], v[64:65], v[148:149] op_sel_hi:[1,0]
	v_pk_mul_f32 v[62:63], v[62:63], v[148:149] op_sel_hi:[1,0]
	v_pk_mul_f32 v[60:61], v[60:61], v[148:149] op_sel_hi:[1,0]
	v_pk_fma_f32 v[106:107], v[106:107], v[148:149], v[150:151]
	v_mov_b32_e32 v148, v149
	v_cvt_pk_bf16_f32 v140, v174, v176
	v_pk_mul_f32 v[58:59], v[58:59], v[148:149] op_sel_hi:[1,0]
	v_pk_mul_f32 v[56:57], v[56:57], v[148:149] op_sel_hi:[1,0]
	v_pk_mul_f32 v[54:55], v[54:55], v[148:149] op_sel_hi:[1,0]
	v_pk_mul_f32 v[52:53], v[52:53], v[148:149] op_sel_hi:[1,0]
	v_pk_mul_f32 v[50:51], v[50:51], v[148:149] op_sel_hi:[1,0]
	v_pk_mul_f32 v[48:49], v[48:49], v[148:149] op_sel_hi:[1,0]
	v_pk_mul_f32 v[46:47], v[46:47], v[148:149] op_sel_hi:[1,0]
	v_pk_mul_f32 v[44:45], v[44:45], v[148:149] op_sel_hi:[1,0]
	v_cvt_pk_bf16_f32 v141, v178, v180
	v_cvt_pk_bf16_f32 v142, v154, v182
	v_cvt_pk_bf16_f32 v143, v156, v184
	v_cvt_pk_bf16_f32 v144, v162, v186
	v_cvt_pk_bf16_f32 v145, v164, v188
	v_cvt_pk_bf16_f32 v146, v170, v190
	v_cvt_pk_bf16_f32 v147, v172, v192
	v_cvt_pk_bf16_f32 v148, v175, v177
	v_cvt_pk_bf16_f32 v149, v179, v181
	v_cvt_pk_bf16_f32 v150, v155, v183
	v_cvt_pk_bf16_f32 v151, v157, v185
	v_cvt_pk_bf16_f32 v152, v163, v187
	v_cvt_pk_bf16_f32 v153, v165, v189
	v_cvt_pk_bf16_f32 v154, v171, v191
	v_cvt_pk_bf16_f32 v155, v173, v193
	v_add_u32_e32 v135, 0x3000, v131
	ds_read2_b64 v[156:159], v135 offset0:128 offset1:132
	v_add_u32_e32 v160, 0x3000, v132
	v_add_u32_e32 v161, 0x3800, v132
	v_add_u32_e32 v162, 0x4000, v132
	s_waitcnt lgkmcnt(0)
	v_mfma_f32_16x16x32_bf16 v[72:75], v[156:159], v[140:143], v[72:75]
	v_mfma_f32_16x16x32_bf16 v[56:59], v[156:159], v[148:151], v[56:59]
	ds_read2_b64 v[156:159], v160 offset0:128 offset1:132
	s_waitcnt lgkmcnt(0)
	v_mfma_f32_16x16x32_bf16 v[68:71], v[156:159], v[140:143], v[68:71]
	v_mfma_f32_16x16x32_bf16 v[52:55], v[156:159], v[148:151], v[52:55]
	ds_read2_b64 v[156:159], v161 offset0:160 offset1:164
	s_waitcnt lgkmcnt(0)
	v_mfma_f32_16x16x32_bf16 v[64:67], v[156:159], v[140:143], v[64:67]
	v_mfma_f32_16x16x32_bf16 v[48:51], v[156:159], v[148:151], v[48:51]
	ds_read2_b64 v[156:159], v162 offset0:192 offset1:196
	s_waitcnt lgkmcnt(0)
	v_mfma_f32_16x16x32_bf16 v[60:63], v[156:159], v[140:143], v[60:63]
	ds_read2_b64 v[140:143], v135 offset0:136 offset1:140
	s_waitcnt lgkmcnt(0)
	v_mfma_f32_16x16x32_bf16 v[72:75], v[140:143], v[144:147], v[72:75]
	v_mfma_f32_16x16x32_bf16 v[56:59], v[140:143], v[152:155], v[56:59]
	ds_read2_b64 v[140:143], v160 offset0:136 offset1:140
	s_waitcnt lgkmcnt(0)
	v_mfma_f32_16x16x32_bf16 v[68:71], v[140:143], v[144:147], v[68:71]
	v_mfma_f32_16x16x32_bf16 v[52:55], v[140:143], v[152:155], v[52:55]
	ds_read2_b64 v[140:143], v161 offset0:168 offset1:172
	s_waitcnt lgkmcnt(0)
	v_mfma_f32_16x16x32_bf16 v[64:67], v[140:143], v[144:147], v[64:67]
	v_mfma_f32_16x16x32_bf16 v[48:51], v[140:143], v[152:155], v[48:51]
	ds_read2_b64 v[140:143], v162 offset0:200 offset1:204
	v_mfma_f32_16x16x32_bf16 v[44:47], v[156:159], v[148:151], v[44:47]
	s_waitcnt lgkmcnt(0)
	v_mfma_f32_16x16x32_bf16 v[60:63], v[140:143], v[144:147], v[60:63]
	v_mfma_f32_16x16x32_bf16 v[44:47], v[140:143], v[152:155], v[44:47]
	s_add_i32 s0, s0, 64
	s_add_i32 s1, s1, 64
	v_lshl_add_u64 v[114:115], v[114:115], 0, s[30:31]
	v_lshl_add_u64 v[116:117], v[116:117], 0, s[30:31]
	s_cmp_eq_u32 s21, s3
	s_mov_b32 s22, s3
	v_mov_b32_e32 v140, v194
	v_mov_b32_e32 v135, v195
	s_cbranch_scc1 .LBB0_1241

; __device__ __forceinline__ void ph_attn(const P& p, int need_ctx, char* smem) {
;     ...
;   for (int task = (blockIdx.x + zz); task < ntask; task += (gridDim.x + zz)) {
;     int b, h, qrow0, nkt;
;     if (task < 512) { b = task >> 6; h = (task >> 4) & 3; int qt = task & 15; qrow0 = b * 2048 + qt * 128; nkt = 36; }
.LBB0_1262:
	s_setprio 0
	s_mov_b64 s[0:1], 0
	v_mov_b32_e32 v126, v196
